# idx scoring: key blocks wholly below the unit's first query use a loop body copy without the causal compare/select
# baseline (speedup 1.0000x reference)
; #define IDX_TOT(j) ({ const f32x4 w4 = wreg[rb * 4 + (j)]; \
;                 const float part = w4[0] * reluf(c[4 * (j)]) + w4[1] * reluf(c[4 * (j) + 1]) + w4[2] * reluf(c[4 * (j) + 2]) + w4[3] * reluf(c[4 * (j) + 3]); swap32_add(part); })
; __device__ __forceinline__ void idx_unit(unsigned char* lds, const bf16_t* P, int b, int qb16, unsigned* bits) {
;     ...
;     for (int blk = wid; blk < nblk; blk += 8) {
;         const int key = blk * 32 + r32;
;         if (blk + 8 < nblk) { const bf16_t* kp = P + (tokb + key + 256) * PW + P_IK + 8 * hi;
; #pragma unroll
;             for (int kk = 0; kk < 4; ++kk) bn[kk] = *(const bf16x8*)(kp + kk * 16); }
; #pragma unroll
;         for (int rb = 0; rb < 4; ++rb) {
;             f32x16 c;
; #pragma unroll
;             for (int r = 0; r < 16; ++r) c[r] = 0.f;
; #pragma unroll
;             for (int kk = 0; kk < 4; ++kk) c = __builtin_amdgcn_mfma_f32_32x32x16_bf16(aq[rb][kk], bk[kk], c, 0, 0, 0);
;             asm volatile("s_nop 15\n\ts_nop 7" : "+v"(c));
;             float tq0, tq1, tq2, tq3;
;     ...
;             tq0 = IDX_TOT(0); tq1 = IDX_TOT(1); tq2 = IDX_TOT(2); tq3 = IDX_TOT(3);
;     ...
;             const float ts0 = hi ? tq2 : tq0, ts1 = hi ? tq3 : tq1;
; #pragma unroll
;             for (int jj = 0; jj < 2; ++jj) { const float tv = jj ? ts1 : ts0; const int q = rb * 4 + 2 * hi + jj;
;                 unsigned short kv = 0;
;                 if (key <= t0 + q) { const _Float16 hv = (_Float16)tv; const unsigned short hb = __builtin_bit_cast(unsigned short, hv); kv = (hb & 0x8000u) ? (unsigned short)~hb : (unsigned short)(hb | 0x8000u); }
;                 sc[q * 4096 + key] = kv; }
;         }
.LBB0_399:
	s_lshl_b32 s6, s10, 5
	s_add_i32 s6, s6, 31
	s_cmp_le_i32 s6, s8
	s_cbranch_scc1 .Lidx_nm
	s_add_i32 s10, s10, 8
	s_cmp_ge_i32 s10, s9
	s_cselect_b64 s[0:1], -1, 0
	s_and_b64 vcc, exec, s[0:1]
	s_cbranch_vccnz .Lidx_go
	v_ashrrev_i32_e32 v181, 31, v180
	v_lshl_add_u64 v[214:215], v[180:181], 0, s[64:65]
	v_mov_b64_e32 v[216:217], s[46:47]
	v_mad_u64_u32 v[216:217], s[6:7], v214, s37, v[216:217]
	v_mad_i32_i24 v217, v215, s37, v217
	v_lshl_add_u64 v[214:215], v[216:217], 0, v[0:1]
	s_mov_b64 s[6:7], 0x161400
	v_lshl_add_u64 v[216:217], v[214:215], 0, s[6:7]
	v_add_co_u32_e32 v214, vcc, 0x161000, v214
	s_nop 1
	v_addc_co_u32_e32 v215, vcc, 0, v215, vcc
	global_load_dwordx4 v[150:153], v[216:217], off offset:32
	global_load_dwordx4 v[146:149], v[216:217], off offset:64
	global_load_dwordx4 v[158:161], v[214:215], off offset:1024
	global_load_dwordx4 v[154:157], v[216:217], off offset:96
.Lidx_go:
	s_waitcnt lgkmcnt(0)
	v_mfma_f32_32x32x16_bf16 v[198:213], v[42:45], v[174:177], 0
	v_max_f32_e32 v2, 0, v2
	v_max_f32_e32 v3, 0, v3
	v_max_f32_e32 v4, 0, v4
	v_max_f32_e32 v5, 0, v5
	v_max_f32_e32 v6, 0, v6
	v_max_f32_e32 v7, 0, v7
	v_max_f32_e32 v8, 0, v8
	v_max_f32_e32 v9, 0, v9
	v_mfma_f32_32x32x16_bf16 v[198:213], v[34:37], v[170:173], v[198:213]
	v_max_f32_e32 v10, 0, v10
	v_max_f32_e32 v11, 0, v11
	v_max_f32_e32 v12, 0, v12
	v_max_f32_e32 v13, 0, v13
	v_max_f32_e32 v14, 0, v14
	v_max_f32_e32 v15, 0, v15
	v_max_f32_e32 v16, 0, v16
	v_max_f32_e32 v17, 0, v17
	v_mfma_f32_32x32x16_bf16 v[198:213], v[38:41], v[166:169], v[198:213]
	v_mul_f32_e32 v3, v139, v3
	v_mul_f32_e32 v7, v143, v7
	v_mul_f32_e32 v11, v135, v11
	v_mul_f32_e32 v15, v131, v15
	v_fmac_f32_e32 v3, v138, v2
	v_fmac_f32_e32 v7, v142, v6
	v_fmac_f32_e32 v11, v134, v10
	v_fmac_f32_e32 v15, v130, v14
	v_mfma_f32_32x32x16_bf16 v[198:213], v[46:49], v[162:165], v[198:213]
	v_fmac_f32_e32 v3, v140, v4
	v_fmac_f32_e32 v7, v144, v8
	v_fmac_f32_e32 v11, v136, v12
	v_fmac_f32_e32 v15, v132, v16
	v_fmac_f32_e32 v3, v141, v5
	v_fmac_f32_e32 v7, v145, v9
	v_fmac_f32_e32 v11, v137, v13
	v_fmac_f32_e32 v15, v133, v17
	s_nop 0
	v_permlane32_swap_b32_e32 v3, v11
	s_nop 0
	v_permlane32_swap_b32_e32 v7, v15
	v_add_f32_e32 v3, v3, v11
	v_add_f32_e32 v7, v7, v15
	v_cvt_f16_f32_e32 v3, v3
	v_cvt_f16_f32_e32 v7, v7
	v_bfe_i32 v2, v3, 15, 1
	v_bfe_i32 v6, v7, 15, 1
	v_bitop3_b32 v3, v3, v2, s101 bitop3:0x1e
	v_bitop3_b32 v7, v7, v6, s101 bitop3:0x1e
	v_cmp_le_i32_e32 vcc, v180, v183
	v_cmp_le_i32_e64 s[6:7], v180, v184
	s_nop 0
	v_cndmask_b32_e32 v3, 0, v3, vcc
	v_cndmask_b32_e64 v7, 0, v7, s[6:7]
	ds_write_b16 v197, v3
	ds_write_b16 v197, v7 offset:8192
	v_mfma_f32_32x32x16_bf16 v[2:17], v[58:61], v[174:177], 0
	v_max_f32_e32 v198, 0, v198
	v_max_f32_e32 v199, 0, v199
	v_max_f32_e32 v200, 0, v200
	v_max_f32_e32 v201, 0, v201
	v_max_f32_e32 v202, 0, v202
	v_max_f32_e32 v203, 0, v203
	v_max_f32_e32 v204, 0, v204
	v_max_f32_e32 v205, 0, v205
	v_mfma_f32_32x32x16_bf16 v[2:17], v[50:53], v[170:173], v[2:17]
	v_max_f32_e32 v206, 0, v206
	v_max_f32_e32 v207, 0, v207
	v_max_f32_e32 v208, 0, v208
	v_max_f32_e32 v209, 0, v209
	v_max_f32_e32 v210, 0, v210
	v_max_f32_e32 v211, 0, v211
	v_max_f32_e32 v212, 0, v212
	v_max_f32_e32 v213, 0, v213
	v_mfma_f32_32x32x16_bf16 v[2:17], v[54:57], v[166:169], v[2:17]
	v_mul_f32_e32 v199, v127, v199
	v_mul_f32_e32 v203, v123, v203
	v_mul_f32_e32 v207, v119, v207
	v_mul_f32_e32 v211, v115, v211
	v_fmac_f32_e32 v199, v126, v198
	v_fmac_f32_e32 v203, v122, v202
	v_fmac_f32_e32 v207, v118, v206
	v_fmac_f32_e32 v211, v114, v210
	v_mfma_f32_32x32x16_bf16 v[2:17], v[62:65], v[162:165], v[2:17]
	v_fmac_f32_e32 v199, v128, v200
	v_fmac_f32_e32 v203, v124, v204
	v_fmac_f32_e32 v207, v120, v208
	v_fmac_f32_e32 v211, v116, v212
	v_fmac_f32_e32 v199, v129, v201
	v_fmac_f32_e32 v203, v125, v205
	v_fmac_f32_e32 v207, v121, v209
	v_fmac_f32_e32 v211, v117, v213
	s_nop 0
	v_permlane32_swap_b32_e32 v199, v207
	s_nop 0
	v_permlane32_swap_b32_e32 v203, v211
	v_add_f32_e32 v199, v199, v207
	v_add_f32_e32 v203, v203, v211
	v_cvt_f16_f32_e32 v199, v199
	v_cvt_f16_f32_e32 v203, v203
	v_bfe_i32 v198, v199, 15, 1
	v_bfe_i32 v202, v203, 15, 1
	v_bitop3_b32 v199, v199, v198, s101 bitop3:0x1e
	v_bitop3_b32 v203, v203, v202, s101 bitop3:0x1e
	v_cmp_le_i32_e32 vcc, v180, v185
	v_cmp_le_i32_e64 s[6:7], v180, v187
	s_nop 0
	v_cndmask_b32_e32 v199, 0, v199, vcc
	v_cndmask_b32_e64 v203, 0, v203, s[6:7]
	ds_write_b16 v197, v199 offset:32768
	ds_write_b16 v197, v203 offset:40960
	v_mfma_f32_32x32x16_bf16 v[198:213], v[74:77], v[174:177], 0
	v_max_f32_e32 v2, 0, v2
	v_max_f32_e32 v3, 0, v3
	v_max_f32_e32 v4, 0, v4
	v_max_f32_e32 v5, 0, v5
	v_max_f32_e32 v6, 0, v6
	v_max_f32_e32 v7, 0, v7
	v_max_f32_e32 v8, 0, v8
	v_max_f32_e32 v9, 0, v9
	v_mfma_f32_32x32x16_bf16 v[198:213], v[66:69], v[170:173], v[198:213]
	v_max_f32_e32 v10, 0, v10
	v_max_f32_e32 v11, 0, v11
	v_max_f32_e32 v12, 0, v12
	v_max_f32_e32 v13, 0, v13
	v_max_f32_e32 v14, 0, v14
	v_max_f32_e32 v15, 0, v15
	v_max_f32_e32 v16, 0, v16
	v_max_f32_e32 v17, 0, v17
	v_mfma_f32_32x32x16_bf16 v[198:213], v[70:73], v[166:169], v[198:213]
	v_mul_f32_e32 v3, v111, v3
	v_mul_f32_e32 v7, v107, v7
	v_mul_f32_e32 v11, v103, v11
	v_mul_f32_e32 v15, v99, v15
	v_fmac_f32_e32 v3, v110, v2
	v_fmac_f32_e32 v7, v106, v6
	v_fmac_f32_e32 v11, v102, v10
	v_fmac_f32_e32 v15, v98, v14
	v_mfma_f32_32x32x16_bf16 v[198:213], v[78:81], v[162:165], v[198:213]
	v_fmac_f32_e32 v3, v112, v4
	v_fmac_f32_e32 v7, v108, v8
	v_fmac_f32_e32 v11, v104, v12
	v_fmac_f32_e32 v15, v100, v16
	v_fmac_f32_e32 v3, v113, v5
	v_fmac_f32_e32 v7, v109, v9
	v_fmac_f32_e32 v11, v105, v13
	v_fmac_f32_e32 v15, v101, v17
	s_nop 0
	v_permlane32_swap_b32_e32 v3, v11
	s_nop 0
	v_permlane32_swap_b32_e32 v7, v15
	v_add_f32_e32 v3, v3, v11
	v_add_f32_e32 v7, v7, v15
	v_cvt_f16_f32_e32 v3, v3
	v_cvt_f16_f32_e32 v7, v7
	v_bfe_i32 v2, v3, 15, 1
	v_bfe_i32 v6, v7, 15, 1
	v_bitop3_b32 v3, v3, v2, s101 bitop3:0x1e
	v_bitop3_b32 v7, v7, v6, s101 bitop3:0x1e
	v_cmp_le_i32_e32 vcc, v180, v192
	v_cmp_le_i32_e64 s[6:7], v180, v193
	s_nop 0
	v_cndmask_b32_e32 v3, 0, v3, vcc
	v_cndmask_b32_e64 v7, 0, v7, s[6:7]
	ds_write_b16 v196, v3
	ds_write_b16 v196, v7 offset:8192
	s_waitcnt vmcnt(0)
; #define IDX_TOT(j) ({ const f32x4 w4 = wreg[rb * 4 + (j)]; \
;                 const float part = w4[0] * reluf(c[4 * (j)]) + w4[1] * reluf(c[4 * (j) + 1]) + w4[2] * reluf(c[4 * (j) + 2]) + w4[3] * reluf(c[4 * (j) + 3]); swap32_add(part); })
; __device__ __forceinline__ void idx_unit(unsigned char* lds, const bf16_t* P, int b, int qb16, unsigned* bits) {
;     ...
;         for (int rb = 0; rb < 4; ++rb) {
;             f32x16 c;
; #pragma unroll
;             for (int r = 0; r < 16; ++r) c[r] = 0.f;
; #pragma unroll
;             for (int kk = 0; kk < 4; ++kk) c = __builtin_amdgcn_mfma_f32_32x32x16_bf16(aq[rb][kk], bk[kk], c, 0, 0, 0);
;             asm volatile("s_nop 15\n\ts_nop 7" : "+v"(c));
;             float tq0, tq1, tq2, tq3;
;     ...
;             tq0 = IDX_TOT(0); tq1 = IDX_TOT(1); tq2 = IDX_TOT(2); tq3 = IDX_TOT(3);
;     ...
;             const float ts0 = hi ? tq2 : tq0, ts1 = hi ? tq3 : tq1;
; #pragma unroll
;             for (int jj = 0; jj < 2; ++jj) { const float tv = jj ? ts1 : ts0; const int q = rb * 4 + 2 * hi + jj;
;                 unsigned short kv = 0;
;                 if (key <= t0 + q) { const _Float16 hv = (_Float16)tv; const unsigned short hb = __builtin_bit_cast(unsigned short, hv); kv = (hb & 0x8000u) ? (unsigned short)~hb : (unsigned short)(hb | 0x8000u); }
;                 sc[q * 4096 + key] = kv; }
;         }
; #pragma unroll
;         for (int kk = 0; kk < 4; ++kk) bk[kk] = bn[kk];
	v_mov_b64_e32 v[162:163], v[154:155]
	v_mov_b64_e32 v[164:165], v[156:157]
	v_mov_b64_e32 v[166:167], v[146:147]
	v_mov_b64_e32 v[168:169], v[148:149]
	v_mov_b64_e32 v[170:171], v[150:151]
	v_mov_b64_e32 v[172:173], v[152:153]
	v_mov_b64_e32 v[174:175], v[158:159]
	v_mov_b64_e32 v[176:177], v[160:161]
	s_nop 1
	v_mfma_f32_32x32x16_bf16 v[2:17], v[26:29], v[174:177], 0
	v_max_f32_e32 v198, 0, v198
	v_max_f32_e32 v199, 0, v199
	v_max_f32_e32 v200, 0, v200
	v_max_f32_e32 v201, 0, v201
	v_max_f32_e32 v202, 0, v202
	v_max_f32_e32 v203, 0, v203
	v_max_f32_e32 v204, 0, v204
	v_max_f32_e32 v205, 0, v205
	v_mfma_f32_32x32x16_bf16 v[2:17], v[18:21], v[170:173], v[2:17]
	v_max_f32_e32 v206, 0, v206
	v_max_f32_e32 v207, 0, v207
	v_max_f32_e32 v208, 0, v208
	v_max_f32_e32 v209, 0, v209
	v_max_f32_e32 v210, 0, v210
	v_max_f32_e32 v211, 0, v211
	v_max_f32_e32 v212, 0, v212
	v_max_f32_e32 v213, 0, v213
	v_mfma_f32_32x32x16_bf16 v[2:17], v[22:25], v[166:169], v[2:17]
	v_mul_f32_e32 v199, v95, v199
	v_mul_f32_e32 v203, v91, v203
	v_mul_f32_e32 v207, v87, v207
	v_mul_f32_e32 v211, v83, v211
	v_fmac_f32_e32 v199, v94, v198
	v_fmac_f32_e32 v203, v90, v202
	v_fmac_f32_e32 v207, v86, v206
	v_fmac_f32_e32 v211, v82, v210
	v_mfma_f32_32x32x16_bf16 v[2:17], v[30:33], v[162:165], v[2:17]
	v_fmac_f32_e32 v199, v96, v200
	v_fmac_f32_e32 v203, v92, v204
	v_fmac_f32_e32 v207, v88, v208
	v_fmac_f32_e32 v211, v84, v212
	v_fmac_f32_e32 v199, v97, v201
	v_fmac_f32_e32 v203, v93, v205
	v_fmac_f32_e32 v207, v89, v209
	v_fmac_f32_e32 v211, v85, v213
	s_nop 0
	v_permlane32_swap_b32_e32 v199, v207
	s_nop 0
	v_permlane32_swap_b32_e32 v203, v211
	v_add_f32_e32 v199, v199, v207
	v_add_f32_e32 v203, v203, v211
	v_cvt_f16_f32_e32 v199, v199
	v_cvt_f16_f32_e32 v203, v203
	v_bfe_i32 v198, v199, 15, 1
	v_bfe_i32 v202, v203, 15, 1
	v_bitop3_b32 v199, v199, v198, s101 bitop3:0x1e
	v_bitop3_b32 v203, v203, v202, s101 bitop3:0x1e
	v_cmp_le_i32_e32 vcc, v180, v194
	v_cmp_le_i32_e64 s[6:7], v180, v195
	s_nop 0
	v_cndmask_b32_e32 v199, 0, v199, vcc
	v_cndmask_b32_e64 v203, 0, v203, s[6:7]
	ds_write_b16 v196, v199 offset:32768
	ds_write_b16 v196, v203 offset:40960
	v_add_u32_e32 v180, 0x100, v180
	v_add_u32_e32 v196, 0x200, v196
	v_add_u32_e32 v197, 0x200, v197
	s_and_b64 vcc, exec, s[0:1]
	s_cbranch_vccz .LBB0_399
	s_branch .LBB0_409

; #define IDX_TOT(j) ({ const f32x4 w4 = wreg[rb * 4 + (j)]; \
;                 const float part = w4[0] * reluf(c[4 * (j)]) + w4[1] * reluf(c[4 * (j) + 1]) + w4[2] * reluf(c[4 * (j) + 2]) + w4[3] * reluf(c[4 * (j) + 3]); swap32_add(part); })
; __device__ __forceinline__ void idx_unit(unsigned char* lds, const bf16_t* P, int b, int qb16, unsigned* bits) {
;     ...
;         for (int rb = 0; rb < 4; ++rb) {
;             f32x16 c;
; #pragma unroll
;             for (int r = 0; r < 16; ++r) c[r] = 0.f;
; #pragma unroll
;             for (int kk = 0; kk < 4; ++kk) c = __builtin_amdgcn_mfma_f32_32x32x16_bf16(aq[rb][kk], bk[kk], c, 0, 0, 0);
;             asm volatile("s_nop 15\n\ts_nop 7" : "+v"(c));
;             float tq0, tq1, tq2, tq3;
;     ...
;             tq0 = IDX_TOT(0); tq1 = IDX_TOT(1); tq2 = IDX_TOT(2); tq3 = IDX_TOT(3);
;     ...
;             const float ts0 = hi ? tq2 : tq0, ts1 = hi ? tq3 : tq1;
; #pragma unroll
;             for (int jj = 0; jj < 2; ++jj) { const float tv = jj ? ts1 : ts0; const int q = rb * 4 + 2 * hi + jj;
;                 unsigned short kv = 0;
;                 if (key <= t0 + q) { const _Float16 hv = (_Float16)tv; const unsigned short hb = __builtin_bit_cast(unsigned short, hv); kv = (hb & 0x8000u) ? (unsigned short)~hb : (unsigned short)(hb | 0x8000u); }
;                 sc[q * 4096 + key] = kv; }
;         }
; #pragma unroll
;         for (int kk = 0; kk < 4; ++kk) bk[kk] = bn[kk];
.Lidx_go_nm:
	s_waitcnt lgkmcnt(0)
	v_mfma_f32_32x32x16_bf16 v[198:213], v[42:45], v[174:177], 0
	v_max_f32_e32 v2, 0, v2
	v_max_f32_e32 v3, 0, v3
	v_max_f32_e32 v4, 0, v4
	v_max_f32_e32 v5, 0, v5
	v_max_f32_e32 v6, 0, v6
	v_max_f32_e32 v7, 0, v7
	v_max_f32_e32 v8, 0, v8
	v_max_f32_e32 v9, 0, v9
	v_mfma_f32_32x32x16_bf16 v[198:213], v[34:37], v[170:173], v[198:213]
	v_max_f32_e32 v10, 0, v10
	v_max_f32_e32 v11, 0, v11
	v_max_f32_e32 v12, 0, v12
	v_max_f32_e32 v13, 0, v13
	v_max_f32_e32 v14, 0, v14
	v_max_f32_e32 v15, 0, v15
	v_max_f32_e32 v16, 0, v16
	v_max_f32_e32 v17, 0, v17
	v_mfma_f32_32x32x16_bf16 v[198:213], v[38:41], v[166:169], v[198:213]
	v_mul_f32_e32 v3, v139, v3
	v_mul_f32_e32 v7, v143, v7
	v_mul_f32_e32 v11, v135, v11
	v_mul_f32_e32 v15, v131, v15
	v_fmac_f32_e32 v3, v138, v2
	v_fmac_f32_e32 v7, v142, v6
	v_fmac_f32_e32 v11, v134, v10
	v_fmac_f32_e32 v15, v130, v14
	v_mfma_f32_32x32x16_bf16 v[198:213], v[46:49], v[162:165], v[198:213]
	v_fmac_f32_e32 v3, v140, v4
	v_fmac_f32_e32 v7, v144, v8
	v_fmac_f32_e32 v11, v136, v12
	v_fmac_f32_e32 v15, v132, v16
	v_fmac_f32_e32 v3, v141, v5
	v_fmac_f32_e32 v7, v145, v9
	v_fmac_f32_e32 v11, v137, v13
	v_fmac_f32_e32 v15, v133, v17
	s_nop 0
	v_permlane32_swap_b32_e32 v3, v11
	s_nop 0
	v_permlane32_swap_b32_e32 v7, v15
	v_add_f32_e32 v3, v3, v11
	v_add_f32_e32 v7, v7, v15
	v_cvt_f16_f32_e32 v3, v3
	v_cvt_f16_f32_e32 v7, v7
	v_bfe_i32 v2, v3, 15, 1
	v_bfe_i32 v6, v7, 15, 1
	v_bitop3_b32 v3, v3, v2, s101 bitop3:0x1e
	v_bitop3_b32 v7, v7, v6, s101 bitop3:0x1e
	ds_write_b16 v197, v3
	ds_write_b16 v197, v7 offset:8192
	v_mfma_f32_32x32x16_bf16 v[2:17], v[58:61], v[174:177], 0
	v_max_f32_e32 v198, 0, v198
	v_max_f32_e32 v199, 0, v199
	v_max_f32_e32 v200, 0, v200
	v_max_f32_e32 v201, 0, v201
	v_max_f32_e32 v202, 0, v202
	v_max_f32_e32 v203, 0, v203
	v_max_f32_e32 v204, 0, v204
	v_max_f32_e32 v205, 0, v205
	v_mfma_f32_32x32x16_bf16 v[2:17], v[50:53], v[170:173], v[2:17]
	v_max_f32_e32 v206, 0, v206
	v_max_f32_e32 v207, 0, v207
	v_max_f32_e32 v208, 0, v208
	v_max_f32_e32 v209, 0, v209
	v_max_f32_e32 v210, 0, v210
	v_max_f32_e32 v211, 0, v211
	v_max_f32_e32 v212, 0, v212
	v_max_f32_e32 v213, 0, v213
	v_mfma_f32_32x32x16_bf16 v[2:17], v[54:57], v[166:169], v[2:17]
	v_mul_f32_e32 v199, v127, v199
	v_mul_f32_e32 v203, v123, v203
	v_mul_f32_e32 v207, v119, v207
	v_mul_f32_e32 v211, v115, v211
	v_fmac_f32_e32 v199, v126, v198
	v_fmac_f32_e32 v203, v122, v202
	v_fmac_f32_e32 v207, v118, v206
	v_fmac_f32_e32 v211, v114, v210
	v_mfma_f32_32x32x16_bf16 v[2:17], v[62:65], v[162:165], v[2:17]
	v_fmac_f32_e32 v199, v128, v200
	v_fmac_f32_e32 v203, v124, v204
	v_fmac_f32_e32 v207, v120, v208
	v_fmac_f32_e32 v211, v116, v212
	v_fmac_f32_e32 v199, v129, v201
	v_fmac_f32_e32 v203, v125, v205
	v_fmac_f32_e32 v207, v121, v209
	v_fmac_f32_e32 v211, v117, v213
	s_nop 0
	v_permlane32_swap_b32_e32 v199, v207
	s_nop 0
	v_permlane32_swap_b32_e32 v203, v211
	v_add_f32_e32 v199, v199, v207
	v_add_f32_e32 v203, v203, v211
	v_cvt_f16_f32_e32 v199, v199
	v_cvt_f16_f32_e32 v203, v203
	v_bfe_i32 v198, v199, 15, 1
	v_bfe_i32 v202, v203, 15, 1
	v_bitop3_b32 v199, v199, v198, s101 bitop3:0x1e
	v_bitop3_b32 v203, v203, v202, s101 bitop3:0x1e
	ds_write_b16 v197, v199 offset:32768
	ds_write_b16 v197, v203 offset:40960
	v_mfma_f32_32x32x16_bf16 v[198:213], v[74:77], v[174:177], 0
	v_max_f32_e32 v2, 0, v2
	v_max_f32_e32 v3, 0, v3
	v_max_f32_e32 v4, 0, v4
	v_max_f32_e32 v5, 0, v5
	v_max_f32_e32 v6, 0, v6
	v_max_f32_e32 v7, 0, v7
	v_max_f32_e32 v8, 0, v8
	v_max_f32_e32 v9, 0, v9
	v_mfma_f32_32x32x16_bf16 v[198:213], v[66:69], v[170:173], v[198:213]
	v_max_f32_e32 v10, 0, v10
	v_max_f32_e32 v11, 0, v11
	v_max_f32_e32 v12, 0, v12
	v_max_f32_e32 v13, 0, v13
	v_max_f32_e32 v14, 0, v14
	v_max_f32_e32 v15, 0, v15
	v_max_f32_e32 v16, 0, v16
	v_max_f32_e32 v17, 0, v17
	v_mfma_f32_32x32x16_bf16 v[198:213], v[70:73], v[166:169], v[198:213]
	v_mul_f32_e32 v3, v111, v3
	v_mul_f32_e32 v7, v107, v7
	v_mul_f32_e32 v11, v103, v11
	v_mul_f32_e32 v15, v99, v15
	v_fmac_f32_e32 v3, v110, v2
	v_fmac_f32_e32 v7, v106, v6
	v_fmac_f32_e32 v11, v102, v10
	v_fmac_f32_e32 v15, v98, v14
	v_mfma_f32_32x32x16_bf16 v[198:213], v[78:81], v[162:165], v[198:213]
	v_fmac_f32_e32 v3, v112, v4
	v_fmac_f32_e32 v7, v108, v8
	v_fmac_f32_e32 v11, v104, v12
	v_fmac_f32_e32 v15, v100, v16
	v_fmac_f32_e32 v3, v113, v5
	v_fmac_f32_e32 v7, v109, v9
	v_fmac_f32_e32 v11, v105, v13
	v_fmac_f32_e32 v15, v101, v17
	s_nop 0
	v_permlane32_swap_b32_e32 v3, v11
	s_nop 0
	v_permlane32_swap_b32_e32 v7, v15
	v_add_f32_e32 v3, v3, v11
	v_add_f32_e32 v7, v7, v15
	v_cvt_f16_f32_e32 v3, v3
	v_cvt_f16_f32_e32 v7, v7
	v_bfe_i32 v2, v3, 15, 1
	v_bfe_i32 v6, v7, 15, 1
	v_bitop3_b32 v3, v3, v2, s101 bitop3:0x1e
	v_bitop3_b32 v7, v7, v6, s101 bitop3:0x1e
	ds_write_b16 v196, v3
	ds_write_b16 v196, v7 offset:8192
	s_waitcnt vmcnt(0)
	v_mov_b64_e32 v[162:163], v[154:155]
	v_mov_b64_e32 v[164:165], v[156:157]
	v_mov_b64_e32 v[166:167], v[146:147]
	v_mov_b64_e32 v[168:169], v[148:149]
	v_mov_b64_e32 v[170:171], v[150:151]
	v_mov_b64_e32 v[172:173], v[152:153]
	v_mov_b64_e32 v[174:175], v[158:159]
	v_mov_b64_e32 v[176:177], v[160:161]
	s_nop 1
	v_mfma_f32_32x32x16_bf16 v[2:17], v[26:29], v[174:177], 0
	v_max_f32_e32 v198, 0, v198
	v_max_f32_e32 v199, 0, v199
	v_max_f32_e32 v200, 0, v200
	v_max_f32_e32 v201, 0, v201
	v_max_f32_e32 v202, 0, v202
	v_max_f32_e32 v203, 0, v203
	v_max_f32_e32 v204, 0, v204
	v_max_f32_e32 v205, 0, v205
	v_mfma_f32_32x32x16_bf16 v[2:17], v[18:21], v[170:173], v[2:17]
	v_max_f32_e32 v206, 0, v206
	v_max_f32_e32 v207, 0, v207
	v_max_f32_e32 v208, 0, v208
	v_max_f32_e32 v209, 0, v209
	v_max_f32_e32 v210, 0, v210
	v_max_f32_e32 v211, 0, v211
	v_max_f32_e32 v212, 0, v212
	v_max_f32_e32 v213, 0, v213
	v_mfma_f32_32x32x16_bf16 v[2:17], v[22:25], v[166:169], v[2:17]
	v_mul_f32_e32 v199, v95, v199
	v_mul_f32_e32 v203, v91, v203
	v_mul_f32_e32 v207, v87, v207
	v_mul_f32_e32 v211, v83, v211
	v_fmac_f32_e32 v199, v94, v198
	v_fmac_f32_e32 v203, v90, v202
	v_fmac_f32_e32 v207, v86, v206
	v_fmac_f32_e32 v211, v82, v210
	v_mfma_f32_32x32x16_bf16 v[2:17], v[30:33], v[162:165], v[2:17]
	v_fmac_f32_e32 v199, v96, v200
	v_fmac_f32_e32 v203, v92, v204
	v_fmac_f32_e32 v207, v88, v208
	v_fmac_f32_e32 v211, v84, v212
	v_fmac_f32_e32 v199, v97, v201
	v_fmac_f32_e32 v203, v93, v205
	v_fmac_f32_e32 v207, v89, v209
	v_fmac_f32_e32 v211, v85, v213
	s_nop 0
	v_permlane32_swap_b32_e32 v199, v207
	s_nop 0
	v_permlane32_swap_b32_e32 v203, v211
	v_add_f32_e32 v199, v199, v207
	v_add_f32_e32 v203, v203, v211
	v_cvt_f16_f32_e32 v199, v199
	v_cvt_f16_f32_e32 v203, v203
	v_bfe_i32 v198, v199, 15, 1
	v_bfe_i32 v202, v203, 15, 1
	v_bitop3_b32 v199, v199, v198, s101 bitop3:0x1e
	v_bitop3_b32 v203, v203, v202, s101 bitop3:0x1e
	ds_write_b16 v196, v199 offset:32768
	ds_write_b16 v196, v203 offset:40960
	v_add_u32_e32 v180, 0x100, v180
	v_add_u32_e32 v196, 0x200, v196
	v_add_u32_e32 v197, 0x200, v197
	s_and_b64 vcc, exec, s[0:1]
	s_cbranch_vccz .LBB0_399
